# strategy 7: + NA PV loop packed v_pk_mul_f32 (O rescale between MFMAs) split into scalar v_mul_f32 pairs
# speedup vs baseline: 1.0142x; 1.0142x over previous
; #define LAS __attribute__((address_space(3)))
; __device__ __forceinline__ unsigned cvt_pk_bf16(float lo, float hi) { unsigned r; asm("v_cvt_pk_bf16_f32 %0, %1, %2" : "=v"(r) : "v"(lo), "v"(hi)); return r; }
; __device__ void na_item(KParams p, int l, int item, LAS unsigned char* lds) {
;     ...
;                     float mx = s2[0];
; #pragma unroll
;                     for (int i = 1; i < 8; ++i) mx = fmaxf(mx, s2[i]);
;                     mx = rowmax4(mx);
;                     const float m_new = fmaxf(m_run[t], mx);
;                     const float m_safe = (m_new == -INFINITY) ? 0.f : m_new;
;                     alpha[t] = __builtin_amdgcn_exp2f(m_run[t] - m_safe);
;                     float ps = 0.f; float pe[8];
; #pragma unroll
;                     for (int i = 0; i < 8; ++i) { pe[i] = __builtin_amdgcn_exp2f(s2[i] - m_safe); ps += pe[i]; }
;                     l_run[t] = l_run[t] * alpha[t] + ps; m_run[t] = m_new;
;                     u32x4 pw; pw.x = cvt_pk_bf16(pe[0], pe[1]); pw.y = cvt_pk_bf16(pe[2], pe[3]); pw.z = cvt_pk_bf16(pe[4], pe[5]); pw.w = cvt_pk_bf16(pe[6], pe[7]);
;                     pb[t] = __builtin_bit_cast(bf16x8, pw);
;                 }
; #pragma unroll
;                 for (int m = 0; m < 8; ++m) {
;                     const u32x2 a0 = *(const LAS u32x2*)(VT + (16 * m + fr) * VS + ((k0 + 4 * fq) ^ (8 * m))), a1 = *(const LAS u32x2*)(VT + (16 * m + fr) * VS + ((k0 + 16 + 4 * fq) ^ (8 * m)));
;                     u32x4 aw; aw.x = a0.x; aw.y = a0.y; aw.z = a1.x; aw.w = a1.y;
; #pragma unroll
;                     for (int t = 0; t < 2; ++t) { O[t][m] *= alpha[t]; O[t][m] = __builtin_amdgcn_mfma_f32_16x16x32_bf16(__builtin_bit_cast(bf16x8, aw), pb[t], O[t][m], 0, 0, 0); }
;                 }
.LBB0_226:
	s_nop 3
	v_sub_f32_e32 v118, v232, v142
	v_exp_f32_e32 v124, v118
	v_add_f32_e32 v118, 0, v143
	v_add_f32_e32 v118, v138, v118
	v_add_f32_e32 v118, v139, v118
	v_add_f32_e32 v118, v140, v118
	v_add_f32_e32 v118, v141, v118
	v_add_f32_e32 v118, v145, v118
	v_add_f32_e32 v118, v147, v118
	v_add_f32_e32 v122, v148, v118
	v_max_f32_e32 v118, v149, v149
	v_max_f32_e32 v119, v144, v144
	v_max_f32_e32 v118, v119, v118
	v_max3_f32 v118, v118, v136, v137
	v_max3_f32 v118, v118, v128, v129
	v_max3_f32 v118, v118, v134, v135
	v_mov_b32_e32 v119, v118
	s_nop 1
	v_permlane16_swap_b32_e32 v118, v119
	v_max_f32_e32 v119, v119, v119
	v_max_f32_e32 v118, v118, v118
	v_max_f32_e32 v118, v118, v119
	v_mov_b32_e32 v119, v118
	s_nop 1
	v_permlane32_swap_b32_e32 v118, v119
	v_max3_f32 v125, v231, v118, v119
	v_cmp_neq_f32_e32 vcc, s92, v125
	v_mul_f32_e32 v112, v124, v112
	v_mul_f32_e32 v113, v124, v113
	v_mul_f32_e32 v110, v124, v110
	v_mul_f32_e32 v111, v124, v111
	v_cndmask_b32_e32 v118, 0, v125, vcc
	v_sub_f32_e32 v119, v231, v118
	v_exp_f32_e32 v126, v119
	v_sub_f32_e32 v119, v144, v118
	v_exp_f32_e32 v119, v119
	v_sub_f32_e32 v121, v149, v118
	v_exp_f32_e32 v121, v121
	v_sub_f32_e32 v123, v136, v118
	v_exp_f32_e32 v127, v123
	v_sub_f32_e32 v123, v137, v118
	v_exp_f32_e32 v130, v123
	v_sub_f32_e32 v123, v128, v118
	v_add_f32_e32 v120, 0, v119
	v_exp_f32_e32 v128, v123
	v_sub_f32_e32 v123, v129, v118
	v_add_f32_e32 v120, v121, v120
	v_exp_f32_e32 v129, v123
	v_sub_f32_e32 v123, v134, v118
	v_add_f32_e32 v120, v127, v120
	v_exp_f32_e32 v131, v123
	v_sub_f32_e32 v118, v135, v118
	v_add_f32_e32 v120, v130, v120
	v_exp_f32_e32 v132, v118
	v_add_f32_e32 v120, v128, v120
	v_add_f32_e32 v120, v129, v120
	v_add_f32_e32 v120, v131, v120
	v_cvt_pk_bf16_f32 v118, v119, v121
	v_cvt_pk_bf16_f32 v119, v127, v130
	v_add_u32_e32 v127, v233, v180
	v_add_f32_e32 v123, v132, v120
	v_cvt_pk_bf16_f32 v120, v128, v129
	v_lshl_add_u32 v128, v127, 1, v230
	v_add_u32_e32 v128, 0x4000, v128
	v_cvt_pk_bf16_f32 v121, v131, v132
	ds_read2_b64 v[128:131], v128 offset0:128 offset1:132
	v_add_u32_e32 v132, v233, v187
	v_mul_f32_e32 v64, v126, v64
	v_mul_f32_e32 v65, v126, v65
	v_mul_f32_e32 v62, v126, v62
	v_mul_f32_e32 v63, v126, v63
	s_waitcnt lgkmcnt(0)
	v_mfma_f32_16x16x32_bf16 v[110:113], v[128:131], v[114:117], v[110:113]
	v_mul_f32_e64 v108, v108, v124
	v_mul_f32_e64 v109, v109, v124
	v_mul_f32_e32 v106, v124, v106
	v_mul_f32_e32 v107, v124, v107
	v_mul_f32_e32 v60, v126, v60
	v_mul_f32_e32 v61, v126, v61
	v_mfma_f32_16x16x32_bf16 v[62:65], v[128:131], v[118:121], v[62:65]
	v_xor_b32_e32 v128, 8, v127
	v_xor_b32_e32 v130, 8, v132
	v_lshl_add_u32 v128, v128, 1, v230
	v_lshl_add_u32 v130, v130, 1, v230
	ds_read_b64 v[128:129], v128 offset:19712
	ds_read_b64 v[130:131], v130 offset:19712
	v_mul_f32_e32 v58, v126, v58
	v_mul_f32_e32 v59, v126, v59
	s_waitcnt lgkmcnt(0)
	v_mfma_f32_16x16x32_bf16 v[106:109], v[128:131], v[114:117], v[106:109]
	v_mul_f32_e64 v104, v104, v124
	v_mul_f32_e64 v105, v105, v124
	v_mul_f32_e32 v102, v124, v102
	v_mul_f32_e32 v103, v124, v103
	v_mul_f32_e32 v56, v126, v56
	v_mul_f32_e32 v57, v126, v57
	v_mfma_f32_16x16x32_bf16 v[58:61], v[128:131], v[118:121], v[58:61]
	v_xor_b32_e32 v128, 16, v127
	v_xor_b32_e32 v130, 16, v132
	v_lshl_add_u32 v128, v128, 1, v230
	v_lshl_add_u32 v130, v130, 1, v230
	ds_read_b64 v[128:129], v128 offset:22016
	ds_read_b64 v[130:131], v130 offset:22016
	v_mul_f32_e32 v54, v126, v54
	v_mul_f32_e32 v55, v126, v55
	s_waitcnt lgkmcnt(0)
	v_mfma_f32_16x16x32_bf16 v[102:105], v[128:131], v[114:117], v[102:105]
	v_mul_f32_e64 v88, v88, v124
	v_mul_f32_e64 v89, v89, v124
	v_mul_f32_e32 v86, v124, v86
	v_mul_f32_e32 v87, v124, v87
	v_mul_f32_e32 v52, v126, v52
	v_mul_f32_e32 v53, v126, v53
	v_mfma_f32_16x16x32_bf16 v[54:57], v[128:131], v[118:121], v[54:57]
	v_xor_b32_e32 v128, 24, v127
	v_xor_b32_e32 v130, 24, v132
	v_lshl_add_u32 v128, v128, 1, v230
	v_lshl_add_u32 v130, v130, 1, v230
	ds_read_b64 v[128:129], v128 offset:24320
	ds_read_b64 v[130:131], v130 offset:24320
	v_mul_f32_e32 v50, v126, v50
	v_mul_f32_e32 v51, v126, v51
	s_waitcnt lgkmcnt(0)
	v_mfma_f32_16x16x32_bf16 v[86:89], v[128:131], v[114:117], v[86:89]
	v_mul_f32_e64 v92, v92, v124
	v_mul_f32_e64 v93, v93, v124
	v_mul_f32_e32 v90, v124, v90
	v_mul_f32_e32 v91, v124, v91
	v_mul_f32_e32 v48, v126, v48
	v_mul_f32_e32 v49, v126, v49
	v_mfma_f32_16x16x32_bf16 v[50:53], v[128:131], v[118:121], v[50:53]
	v_xor_b32_e32 v128, 32, v127
	v_xor_b32_e32 v130, 32, v132
	v_lshl_add_u32 v128, v128, 1, v230
	v_lshl_add_u32 v130, v130, 1, v230
	ds_read_b64 v[128:129], v128 offset:26624
	ds_read_b64 v[130:131], v130 offset:26624
	v_mul_f32_e32 v46, v126, v46
	v_mul_f32_e32 v47, v126, v47
	s_waitcnt lgkmcnt(0)
	v_mfma_f32_16x16x32_bf16 v[90:93], v[128:131], v[114:117], v[90:93]
	v_mul_f32_e64 v80, v80, v124
	v_mul_f32_e64 v81, v81, v124
	v_mul_f32_e32 v78, v124, v78
	v_mul_f32_e32 v79, v124, v79
	v_mul_f32_e32 v44, v126, v44
	v_mul_f32_e32 v45, v126, v45
	v_mfma_f32_16x16x32_bf16 v[46:49], v[128:131], v[118:121], v[46:49]
	v_xor_b32_e32 v128, 40, v127
	v_xor_b32_e32 v130, 40, v132
	v_lshl_add_u32 v128, v128, 1, v230
	v_lshl_add_u32 v130, v130, 1, v230
	ds_read_b64 v[128:129], v128 offset:28928
	ds_read_b64 v[130:131], v130 offset:28928
	v_mul_f32_e32 v42, v126, v42
	v_mul_f32_e32 v43, v126, v43
	s_waitcnt lgkmcnt(0)
	v_mfma_f32_16x16x32_bf16 v[78:81], v[128:131], v[114:117], v[78:81]
	v_mul_f32_e64 v40, v40, v126
	v_mul_f32_e64 v41, v41, v126
	v_mul_f32_e32 v38, v126, v38
	v_mul_f32_e32 v39, v126, v39
	v_mul_f32_e32 v72, v124, v72
	v_mul_f32_e32 v73, v124, v73
	v_mfma_f32_16x16x32_bf16 v[42:45], v[128:131], v[118:121], v[42:45]
	v_xor_b32_e32 v128, 48, v127
	v_xor_b32_e32 v130, 48, v132
	v_lshl_add_u32 v128, v128, 1, v230
	v_lshl_add_u32 v130, v130, 1, v230
	ds_read_b64 v[128:129], v128 offset:31232
	ds_read_b64 v[130:131], v130 offset:31232
	v_xor_b32_e32 v127, 56, v127
	v_mul_f32_e32 v70, v124, v70
	v_mul_f32_e32 v71, v124, v71
	v_lshl_add_u32 v127, v127, 1, v230
	s_waitcnt lgkmcnt(0)
	v_mfma_f32_16x16x32_bf16 v[38:41], v[128:131], v[118:121], v[38:41]
	v_mul_f32_e64 v68, v68, v124
	v_mul_f32_e64 v69, v69, v124
	v_mul_f32_e32 v66, v124, v66
	v_mul_f32_e32 v67, v124, v67
	s_and_b64 s[38:39], s[40:41], s[26:27]
	v_mfma_f32_16x16x32_bf16 v[70:73], v[128:131], v[114:117], v[70:73]
	ds_read_b64 v[128:129], v127 offset:33536
	v_xor_b32_e32 v127, 56, v132
	v_lshl_add_u32 v127, v127, 1, v230
	ds_read_b64 v[130:131], v127 offset:33536
	v_mul_f32_e32 v36, v126, v36
	v_mul_f32_e32 v37, v126, v37
	v_mul_f32_e32 v34, v126, v34
	v_mul_f32_e32 v35, v126, v35
	s_waitcnt lgkmcnt(0)
	v_mfma_f32_16x16x32_bf16 v[66:69], v[128:131], v[114:117], v[66:69]
	v_fmac_f32_e32 v122, v168, v124
	v_fmac_f32_e32 v123, v169, v126
	s_mov_b32 s28, 32
	v_mfma_f32_16x16x32_bf16 v[34:37], v[128:131], v[118:121], v[34:37]
	s_mov_b64 s[26:27], 0
	s_and_b64 vcc, exec, s[38:39]
	s_cbranch_vccz .LBB0_228
; __device__ void na_item(KParams p, int l, int item, LAS unsigned char* lds) {
;     ...
;     for (int st = 0; st < nst; ++st) {
;     ...
;                     l_run[t] = l_run[t] * alpha[t] + ps; m_run[t] = m_new;
	v_mov_b32_e32 v168, v122
	v_mov_b32_e32 v169, v123
	v_mov_b32_e32 v232, v146
	v_mov_b32_e32 v231, v125
	s_branch .LBB0_214
